# attention first (diagonal) tile: its four K-fragment LDS reads issued right after the unit barrier, ahead of the next-window prefetch block; on top of v40
# baseline (speedup 1.0000x reference)
; #define LAS __attribute__((address_space(3)))
; __device__ __forceinline__ void attn_phase(LAS unsigned char* lds, const bf16_t* Q, const bf16_t* Kb, const bf16_t* VT, const bf16_t* Zs, bf16_t* OZ, int vcu, int G) {
;     ...
;         ATT_DECODE(unit, h, rowbase, q0b, kw0)
;         const int qblk = unit & 31;
;         const int qb = 8 * qblk + w, q0 = 32 * qb;
;         bf16x8 qf[4];
;         { const bf16_t* qp = Q + (rowbase + q0 + ql) * D + h * 64 + 8 * hi;
; #pragma unroll
;           for (int kk = 0; kk < 4; ++kk) qf[kk] = *(const bf16x8*)(qp + 16 * kk); }
;         u32x2 zz[8];
;         { const bf16_t* zp = Zs + (rowbase + q0 + ql) * D + h * 64 + 4 * hi;
; #pragma unroll
;           for (int g4 = 0; g4 < 4; ++g4) { zz[g4] = *(const u32x2*)(zp + 8 * g4); zz[4 + g4] = *(const u32x2*)(zp + 32 + 8 * g4); } }
;         asm volatile("" ::: "memory");
; #pragma unroll
;         for (int i = 0; i < 6; ++i) { const int idx = tid + NTHR * i, r = idx >> 3, c = idx & 7;
;             *(LAS u32x4*)(KL + r * 128 + ((c ^ ((r >> 1) & 7)) << 4)) = sk[i]; }
; #pragma unroll
;         for (int i = 0; i < 6; ++i) { const int idx = tid + NTHR * i, d = idx / 48, ch = idx % 48;
;             { u32x4 v = sv[i]; const int gp = (2 * ch) ^ (d & 31);
;                 if (d & 1) { const u32x4 t = v; v.x = t.z; v.y = t.w; v.z = t.x; v.w = t.y; }
;                 *(LAS u32x4*)(VL + d * 768 + ((gp & ~1) << 3)) = v; } }
;         __syncthreads();
.LBB0_540:
	s_and_b32 s100, s84, 7
	s_bfe_u32 s99, s84, 0x20005
	s_lshl_b32 s99, s99, 3
	s_or_b32 s100, s100, s99
	s_bfe_u32 s99, s84, 0x20003
	s_lshl_b32 s99, s99, 5
	s_or_b32 s100, s100, s99
	s_bfe_u32 s99, s84, 0x20008
	s_lshl_b32 s99, s99, 7
	s_or_b32 s100, s100, s99
	s_bfe_u32 s99, s84, 0x10007
	s_lshl_b32 s99, s99, 9
	s_or_b32 s100, s100, s99
	s_ashr_i32 s74, s100, 9
	s_ashr_i32 s75, s74, 31
	s_and_b32 s58, s100, 31
	s_lshl_b64 s[78:79], s[74:75], 13
	s_lshl_b32 s74, s58, 3
	s_and_b32 s59, s100, 31
	s_lshl_b32 s81, s58, 8
	s_add_i32 s90, s74, s85
	s_lshl_b32 s91, s59, 3
	s_addk_i32 s81, 0xff80
	s_lshl_b32 s80, s90, 5
	s_add_u32 s74, s78, s80
	s_addc_u32 s75, s79, 0
	v_or_b32_e32 v190, s74, v142
	s_lshl_b32 s74, s100, 1
	s_and_b32 s92, s74, 0x3c0
	s_mov_b32 s72, s100
	s_lshl_b32 s76, s92, 1
	s_add_i32 s84, s84, s3
	s_and_b32 s101, s84, 7
	s_bfe_u32 s99, s84, 0x20005
	s_lshl_b32 s99, s99, 3
	s_or_b32 s101, s101, s99
	s_bfe_u32 s99, s84, 0x20003
	s_lshl_b32 s99, s99, 5
	s_or_b32 s101, s101, s99
	s_bfe_u32 s99, s84, 0x20008
	s_lshl_b32 s99, s99, 7
	s_or_b32 s101, s101, s99
	s_bfe_u32 s99, s84, 0x10007
	s_lshl_b32 s99, s99, 9
	s_or_b32 s101, s101, s99
	v_mov_b32_e32 v191, s75
	s_cmpk_gt_i32 s84, 0x3ff
	v_lshlrev_b64 v[2:3], 11, v[190:191]
	s_cselect_b64 s[74:75], -1, 0
	s_cmpk_lt_i32 s84, 0x400
	v_lshl_add_u64 v[4:5], s[64:65], 0, v[2:3]
	s_mov_b32 s77, s73
	v_lshl_add_u64 v[2:3], s[66:67], 0, v[2:3]
	s_cselect_b32 s72, s101, s72
	v_lshl_add_u64 v[4:5], v[4:5], 0, s[76:77]
	v_lshl_add_u64 v[2:3], v[2:3], 0, s[76:77]
	v_mov_b32_e32 v163, v145
	s_bfe_u32 s77, s72, 0x40005
	s_ashr_i32 s82, s72, 9
	s_lshl_b32 s72, s72, 8
	v_lshl_add_u64 v[4:5], v[4:5], 0, v[144:145]
	v_lshl_add_u64 v[2:3], v[2:3], 0, v[162:163]
	s_ashr_i32 s83, s82, 31
	s_and_b32 s72, s72, 0x1f00
	global_load_dwordx4 v[114:117], v[4:5], off
	global_load_dwordx4 v[118:121], v[4:5], off offset:32
	global_load_dwordx4 v[122:125], v[4:5], off offset:64
	global_load_dwordx4 v[126:129], v[4:5], off offset:96
	global_load_dwordx2 v[192:193], v[2:3], off
	global_load_dwordx2 v[186:187], v[2:3], off offset:16
	global_load_dwordx2 v[182:183], v[2:3], off offset:32
	global_load_dwordx2 v[178:179], v[2:3], off offset:48
	global_load_dwordx2 v[188:189], v[2:3], off offset:64
	global_load_dwordx2 v[184:185], v[2:3], off offset:80
	global_load_dwordx2 v[180:181], v[2:3], off offset:96
	global_load_dwordx2 v[176:177], v[2:3], off offset:112
	s_waitcnt vmcnt(17)
	v_cndmask_b32_e64 v5, v95, v97, s[48:49]
	v_cndmask_b32_e64 v4, v94, v96, s[48:49]
	v_cndmask_b32_e64 v3, v97, v95, s[48:49]
	v_cndmask_b32_e64 v2, v96, v94, s[48:49]
	s_lshl_b64 s[94:95], s[82:83], 13
	s_add_i32 s93, s72, 0xffffff80
	ds_write_b128 v206, v[66:69]
	ds_write_b128 v207, v[70:73]
	ds_write_b128 v206, v[74:77] offset:16384
	ds_write_b128 v208, v[78:81]
	ds_write_b128 v206, v[82:85] offset:32768
	ds_write_b128 v209, v[86:89]
	ds_write_b128 v210, v[2:5] offset:49152
	s_waitcnt vmcnt(16)
	v_cndmask_b32_e64 v5, v91, v93, s[4:5]
	v_cndmask_b32_e64 v4, v90, v92, s[4:5]
	v_cndmask_b32_e64 v3, v93, v91, s[4:5]
	v_cndmask_b32_e64 v2, v92, v90, s[4:5]
	s_cmp_lg_u32 s72, 0
	ds_write_b128 v211, v[2:5] offset:49152
	s_waitcnt vmcnt(15)
	v_cndmask_b32_e64 v5, v103, v105, s[6:7]
	v_cndmask_b32_e64 v4, v102, v104, s[6:7]
	v_cndmask_b32_e64 v3, v105, v103, s[6:7]
	v_cndmask_b32_e64 v2, v104, v102, s[6:7]
	s_cselect_b32 s96, s93, 0
	ds_write_b128 v212, v[2:5] offset:49152
	s_waitcnt vmcnt(14)
	v_cndmask_b32_e64 v5, v99, v101, s[8:9]
	v_cndmask_b32_e64 v4, v98, v100, s[8:9]
	v_cndmask_b32_e64 v3, v101, v99, s[8:9]
	v_cndmask_b32_e64 v2, v100, v98, s[8:9]
	s_ashr_i32 s97, s96, 31
	ds_write_b128 v213, v[2:5] offset:49152
	s_waitcnt vmcnt(13)
	v_cndmask_b32_e64 v5, v111, v113, s[10:11]
	v_cndmask_b32_e64 v4, v110, v112, s[10:11]
	v_cndmask_b32_e64 v3, v113, v111, s[10:11]
	v_cndmask_b32_e64 v2, v112, v110, s[10:11]
	s_add_u32 s94, s94, s96
	ds_write_b128 v214, v[2:5] offset:49152
	s_waitcnt vmcnt(12)
	v_cndmask_b32_e64 v5, v107, v109, s[12:13]
	v_cndmask_b32_e64 v4, v106, v108, s[12:13]
	v_cndmask_b32_e64 v3, v109, v107, s[12:13]
	v_cndmask_b32_e64 v2, v108, v106, s[12:13]
	s_addc_u32 s95, s95, s97
	ds_write_b128 v215, v[2:5] offset:49152
	s_lshl_b32 s72, s77, 7
	v_mov_b32_e32 v5, s95
	v_or_b32_e32 v4, s94, v146
	v_mov_b32_e32 v7, s95
	v_or_b32_e32 v6, s94, v148
	v_lshl_add_u64 v[2:3], v[158:159], 0, s[72:73]
	v_lshlrev_b64 v[4:5], 11, v[4:5]
	v_lshlrev_b64 v[6:7], 11, v[6:7]
	v_lshl_add_u64 v[4:5], v[2:3], 0, v[4:5]
	v_lshl_add_u64 v[6:7], v[2:3], 0, v[6:7]
	s_waitcnt lgkmcnt(0)
	s_barrier
; #define LAS __attribute__((address_space(3)))
; __device__ __forceinline__ void attn_load_k(bf16x8 (&kf)[4], bool in_lds, LAS unsigned char* KL, int kl0, const bf16_t* kg, int ql, int hi) {
;     if (in_lds) { const int r = kl0 + ql; LAS unsigned char* rp = KL + r * 128; const int sw = (r >> 1) & 7;
; #pragma unroll
;         for (int kk = 0; kk < 4; ++kk) kf[kk] = *(const LAS bf16x8*)(rp + (((2 * kk + hi) ^ sw) << 4));
; __device__ __forceinline__ void attn_phase(LAS unsigned char* lds, const bf16_t* Q, const bf16_t* Kb, const bf16_t* VT, const bf16_t* Zs, bf16_t* OZ, int vcu, int G) {
;     ...
;         { const int nu_ = unit + G < NU ? unit + G : unit; ATT_LOAD_STAGE(nu_); }
;         f32x16 o0, o1;
; #pragma unroll
;         for (int i = 0; i < 16; ++i) { o0[i] = 0.f; o1[i] = 0.f; }
;         float carry = 1.f;
	s_cmp_lg_u32 s58, 0
	s_cselect_b32 s99, s81, 0
	s_sub_i32 s99, s80, s99
	v_or_b32_e32 v255, s99, v142
	v_lshl_add_u32 v254, v255, 7, 0
	v_lshrrev_b32_e32 v255, 1, v255
	v_bitop3_b32 v240, v255, v1, 7 bitop3:0x6c
	v_lshl_add_u32 v240, v240, 4, v254
	ds_read_b128 v[240:243], v240
	v_bitop3_b32 v244, v255, v143, 7 bitop3:0x6c
	v_lshl_add_u32 v244, v244, 4, v254
	ds_read_b128 v[244:247], v244
	v_bitop3_b32 v248, v255, v147, 7 bitop3:0x6c
	v_lshl_add_u32 v248, v248, 4, v254
	ds_read_b128 v[248:251], v248
	v_bitop3_b32 v252, v255, v149, 7 bitop3:0x6c
	v_lshl_add_u32 v252, v252, 4, v254
	ds_read_b128 v[252:255], v252
	global_load_dwordx4 v[66:69], v[4:5], off
	global_load_dwordx4 v[70:73], v[6:7], off
	v_lshl_add_u64 v[4:5], s[94:95], 0, v[150:151]
	v_lshl_add_u64 v[6:7], s[94:95], 0, v[152:153]
	v_lshlrev_b64 v[4:5], 11, v[4:5]
	v_lshlrev_b64 v[6:7], 11, v[6:7]
	v_lshl_add_u64 v[4:5], v[2:3], 0, v[4:5]
	v_lshl_add_u64 v[6:7], v[2:3], 0, v[6:7]
	global_load_dwordx4 v[74:77], v[4:5], off
	global_load_dwordx4 v[78:81], v[6:7], off
	v_lshl_add_u64 v[4:5], s[94:95], 0, v[154:155]
	v_lshl_add_u64 v[6:7], s[94:95], 0, v[156:157]
	s_lshl_b32 s72, s77, 20
	s_lshl_b64 s[82:83], s[82:83], 14
	v_lshlrev_b64 v[4:5], 11, v[4:5]
	v_lshlrev_b64 v[6:7], 11, v[6:7]
	s_add_u32 s77, s68, s82
	v_lshl_add_u64 v[4:5], v[2:3], 0, v[4:5]
	v_lshl_add_u64 v[2:3], v[2:3], 0, v[6:7]
	s_addc_u32 s93, s69, s83
	s_lshl_b64 s[82:83], s[96:97], 1
	global_load_dwordx4 v[82:85], v[4:5], off
	global_load_dwordx4 v[86:89], v[2:3], off
	s_add_u32 s82, s77, s82
	v_or_b32_e32 v2, s72, v196
	s_addc_u32 s83, s93, s83
	v_lshlrev_b32_e32 v2, 1, v2
	v_mov_b32_e32 v3, v145
	v_or_b32_e32 v4, s72, v197
	v_lshl_add_u64 v[2:3], s[82:83], 0, v[2:3]
	v_mov_b32_e32 v165, v145
	v_lshlrev_b32_e32 v4, 1, v4
	v_mov_b32_e32 v5, v145
	v_lshl_add_u64 v[2:3], v[2:3], 0, v[164:165]
	v_lshl_add_u64 v[4:5], s[82:83], 0, v[4:5]
	v_mov_b32_e32 v167, v145
	v_lshl_add_u64 v[4:5], v[4:5], 0, v[166:167]
	global_load_dwordx4 v[94:97], v[2:3], off
	global_load_dwordx4 v[90:93], v[4:5], off
	v_or_b32_e32 v2, s72, v198
	v_lshlrev_b32_e32 v2, 1, v2
	v_mov_b32_e32 v3, v145
	v_or_b32_e32 v4, s72, v199
	v_lshl_add_u64 v[2:3], s[82:83], 0, v[2:3]
	v_mov_b32_e32 v169, v145
	v_lshlrev_b32_e32 v4, 1, v4
	v_mov_b32_e32 v5, v145
	v_lshl_add_u64 v[2:3], v[2:3], 0, v[168:169]
	v_lshl_add_u64 v[4:5], s[82:83], 0, v[4:5]
	v_mov_b32_e32 v171, v145
	v_lshl_add_u64 v[4:5], v[4:5], 0, v[170:171]
	global_load_dwordx4 v[102:105], v[2:3], off
	global_load_dwordx4 v[98:101], v[4:5], off
	v_or_b32_e32 v2, s72, v200
	v_lshlrev_b32_e32 v2, 1, v2
	v_mov_b32_e32 v3, v145
	v_or_b32_e32 v4, s72, v201
	v_lshl_add_u64 v[2:3], s[82:83], 0, v[2:3]
	v_mov_b32_e32 v173, v145
	v_lshlrev_b32_e32 v4, 1, v4
	v_mov_b32_e32 v5, v145
	v_lshl_add_u64 v[2:3], v[2:3], 0, v[172:173]
	v_lshl_add_u64 v[4:5], s[82:83], 0, v[4:5]
	v_mov_b32_e32 v175, v145
	v_lshl_add_u64 v[4:5], v[4:5], 0, v[174:175]
	global_load_dwordx4 v[110:113], v[2:3], off
	global_load_dwordx4 v[106:109], v[4:5], off
	s_cmp_lg_u32 s58, 0
	s_cselect_b32 s58, s81, 0
	s_cmp_lt_i32 s80, s58
	s_cbranch_scc1 .LBB0_552
	s_sub_i32 s72, s80, s58
	s_lshr_b32 s77, s72, 2
	v_bitop3_b32 v6, s77, v142, v1 bitop3:0x36
	v_lshlrev_b32_e32 v30, 3, v6
	v_or_b32_e32 v28, s77, v1
	s_waitcnt vmcnt(23) lgkmcnt(0)
	v_mfma_f32_32x32x16_bf16 v[2:17], v[240:243], v[114:117], 0
	v_bitop3_b32 v22, v28, v142, 2 bitop3:0x36
	v_lshlrev_b32_e32 v32, 3, v22
	v_bitop3_b32 v22, v28, v142, 4 bitop3:0x36
	v_lshlrev_b32_e32 v38, 3, v22
	s_waitcnt vmcnt(22) lgkmcnt(1)
	v_mfma_f32_32x32x16_bf16 v[2:17], v[244:247], v[118:121], v[2:17]
	v_bitop3_b32 v18, v28, v142, 6 bitop3:0x36
	v_lshlrev_b32_e32 v39, 3, v18
	v_add_u32_e32 v31, v202, v30
	v_add_u32_e32 v34, v202, v38
	s_waitcnt vmcnt(21) lgkmcnt(1)
	v_mfma_f32_32x32x16_bf16 v[2:17], v[248:251], v[122:125], v[2:17]
	v_add_u32_e32 v36, v202, v39
	v_add_u32_e32 v22, v203, v30
	v_add_u32_e32 v24, v203, v38
	v_add_u32_e32 v33, v202, v32
	ds_read_b64 v[18:19], v31 offset:49152
	ds_read_b64 v[20:21], v33 offset:49152
	ds_read_b64 v[34:35], v34 offset:49152
	ds_read_b64 v[36:37], v36 offset:49152
	v_add_u32_e32 v23, v203, v32
	v_add_u32_e32 v25, v203, v39
	s_waitcnt vmcnt(20) lgkmcnt(4)
	v_mfma_f32_32x32x16_bf16 v[2:17], v[252:255], v[126:129], v[2:17]
	ds_read_b64 v[42:43], v22 offset:24576
	ds_read_b64 v[44:45], v23 offset:24576
	ds_read_b64 v[38:39], v24 offset:24576
	ds_read_b64 v[40:41], v25 offset:24576
	v_and_b32_e32 v48, 64, v216
	v_add_u32_e32 v48, 64, v48
	s_mov_b64 s[80:81], 0
	s_nop 4
	v_min_f32_e64 v3, -v3, s98
	v_exp_f32_e32 v3, v3
	v_min_f32_e64 v4, -v4, s98
	v_exp_f32_e32 v24, v4
	v_add_f32_e32 v22, 1.0, v3
	v_min_f32_e64 v4, -v5, s98
	v_rcp_f32_e32 v22, v22
	v_exp_f32_e32 v5, v4
	v_add_f32_e32 v4, 1.0, v24
	v_mul_f32_e32 v3, v3, v22
	v_rcp_f32_e32 v25, v4
	v_cndmask_b32_e64 v4, 1.0, v3, s[16:17]
	v_add_f32_e32 v3, 1.0, v5
	v_min_f32_e64 v2, -v2, s98
	v_rcp_f32_e32 v3, v3
	v_exp_f32_e32 v2, v2
	v_mul_f32_e32 v24, v24, v25
	v_cndmask_b32_e64 v46, 1.0, v24, s[18:19]
	v_mul_f32_e32 v5, v5, v3
	v_cndmask_b32_e64 v24, 0, v3, s[20:21]
	v_min_f32_e64 v3, -v6, s98
	v_min_f32_e64 v6, -v7, s98
	v_add_f32_e32 v26, 1.0, v2
	v_exp_f32_e32 v3, v3
	v_rcp_f32_e32 v26, v26
	v_exp_f32_e32 v7, v6
	v_add_f32_e32 v6, 1.0, v3
	v_cndmask_b32_e64 v22, 0, v22, s[16:17]
	v_mul_f32_e32 v2, v2, v26
	v_cndmask_b32_e64 v23, 0, v26, s[14:15]
	v_rcp_f32_e32 v26, v6
	v_cndmask_b32_e64 v6, 1.0, v5, s[20:21]
	v_add_f32_e32 v5, 1.0, v7
	v_rcp_f32_e32 v5, v5
	v_mul_f32_e32 v3, v3, v26
	v_cndmask_b32_e64 v3, 1.0, v3, s[22:23]
	v_cndmask_b32_e64 v2, 1.0, v2, s[14:15]
	v_mul_f32_e32 v7, v7, v5
; __device__ __forceinline__ void attn_phase(LAS unsigned char* lds, const bf16_t* Q, const bf16_t* Kb, const bf16_t* VT, const bf16_t* Zs, bf16_t* OZ, int vcu, int G) {
;     ...
;         int kt = qb; bool done = false;
;     ...
;             ATT_TILE(true)
;             if (__all(carry < STOP)) { done = true; break; }
;         }
;     ...
;             ATT_TILE(false)
	v_cndmask_b32_e64 v27, 0, v5, s[24:25]
	v_min_f32_e64 v5, -v8, s98
	v_min_f32_e64 v8, -v9, s98
	v_exp_f32_e32 v5, v5
	v_exp_f32_e32 v8, v8
	v_cndmask_b32_e64 v28, 1.0, v7, s[24:25]
	v_add_f32_e32 v9, 1.0, v5
	v_rcp_f32_e32 v9, v9
	v_add_f32_e32 v7, 1.0, v8
	v_rcp_f32_e32 v7, v7
	v_mul_f32_e32 v3, v3, v28
	v_mul_f32_e32 v5, v5, v9
	v_cndmask_b32_e64 v30, 1.0, v5, s[26:27]
	v_mul_f32_e32 v5, v8, v7
	v_min_f32_e64 v8, -v11, s98
	v_cndmask_b32_e64 v31, 0, v7, s[28:29]
	v_min_f32_e64 v7, -v10, s98
	v_exp_f32_e32 v8, v8
	v_exp_f32_e32 v7, v7
	v_cndmask_b32_e64 v10, 1.0, v5, s[28:29]
	v_cndmask_b32_e64 v29, 0, v9, s[26:27]
	v_add_f32_e32 v5, 1.0, v8
	v_add_f32_e32 v9, 1.0, v7
	v_rcp_f32_e32 v5, v5
	v_rcp_f32_e32 v9, v9
	v_cndmask_b32_e64 v25, 0, v25, s[18:19]
	v_cndmask_b32_e64 v26, 0, v26, s[22:23]
	v_mul_f32_e32 v8, v8, v5
	v_cndmask_b32_e64 v51, 0, v5, s[34:35]
	v_min_f32_e64 v5, -v12, s98
	v_mul_f32_e32 v7, v7, v9
	v_cndmask_b32_e64 v50, 0, v9, s[30:31]
	v_min_f32_e64 v9, -v13, s98
	v_exp_f32_e32 v5, v5
	v_exp_f32_e32 v9, v9
	v_cndmask_b32_e64 v12, 1.0, v8, s[34:35]
	v_add_f32_e32 v11, 1.0, v5
	v_rcp_f32_e32 v11, v11
	v_add_f32_e32 v8, 1.0, v9
	v_rcp_f32_e32 v8, v8
	v_cndmask_b32_e64 v7, 1.0, v7, s[30:31]
	v_mul_f32_e32 v5, v5, v11
	v_cndmask_b32_e64 v52, 0, v11, s[36:37]
	v_cndmask_b32_e64 v11, 1.0, v5, s[36:37]
	v_mul_f32_e32 v5, v9, v8
	v_min_f32_e64 v9, -v15, s98
	v_exp_f32_e32 v9, v9
	v_cndmask_b32_e64 v15, 1.0, v5, s[38:39]
	v_cndmask_b32_e64 v13, 0, v8, s[38:39]
	v_min_f32_e64 v8, -v14, s98
	v_add_f32_e32 v5, 1.0, v9
	v_rcp_f32_e32 v5, v5
	v_exp_f32_e32 v8, v8
	v_mul_f32_e32 v7, v7, v12
	v_mul_f32_e32 v9, v9, v5
	v_cndmask_b32_e64 v32, 0, v5, s[42:43]
	v_min_f32_e64 v5, -v16, s98
	v_min_f32_e64 v16, -v17, s98
	v_exp_f32_e32 v5, v5
	v_exp_f32_e32 v16, v16
	v_add_f32_e32 v14, 1.0, v8
	v_add_f32_e32 v17, 1.0, v5
	v_rcp_f32_e32 v17, v17
	v_add_f32_e32 v33, 1.0, v16
	v_rcp_f32_e32 v33, v33
	v_rcp_f32_e32 v14, v14
	v_mul_f32_e32 v5, v5, v17
	v_cndmask_b32_e64 v47, 1.0, v5, s[44:45]
	v_mul_f32_e32 v5, v16, v33
	v_mul_f32_e32 v8, v8, v14
	v_cndmask_b32_e64 v16, 0, v33, s[46:47]
	v_cndmask_b32_e64 v33, 1.0, v5, s[46:47]
	v_xor_b32_e32 v5, 32, v216
	v_cndmask_b32_e64 v8, 1.0, v8, s[40:41]
	v_cndmask_b32_e64 v9, 1.0, v9, s[42:43]
	v_cmp_lt_i32_e32 vcc, v5, v48
	v_mul_f32_e32 v8, v8, v9
	v_mul_f32_e32 v48, v47, v33
	v_cndmask_b32_e32 v5, v216, v5, vcc
	v_lshlrev_b32_e32 v163, 2, v5
	v_mul_f32_e32 v8, v8, v48
	v_mov_b32_e32 v238, v8
	v_mov_b32_e32 v48, v8
	s_nop 1
	v_permlane32_swap_b32_e32 v238, v48
	s_nop 0
	v_cndmask_b32_e64 v48, v238, v48, s[0:1]
	v_mul_f32_e32 v49, v11, v15
	v_mul_f32_e32 v5, v30, v10
	v_mul_f32_e32 v7, v7, v49
	v_mul_f32_e32 v3, v3, v5
	v_mov_b32_e32 v238, v7
	v_mov_b32_e32 v53, v7
	s_nop 1
	v_permlane32_swap_b32_e32 v238, v53
	s_nop 0
	v_cndmask_b32_e64 v53, v238, v53, s[0:1]
	v_mov_b32_e32 v238, v3
	v_mov_b32_e32 v5, v3
	s_nop 1
	v_permlane32_swap_b32_e32 v238, v5
	s_nop 0
	v_cndmask_b32_e64 v5, v238, v5, s[0:1]
	s_waitcnt lgkmcnt(2)
	v_cndmask_b32_e64 v49, 1.0, v48, s[0:1]
	v_mul_f32_e32 v33, v33, v49
	v_mul_f32_e32 v47, v47, v33
	v_mul_f32_e32 v54, v9, v47
	v_mul_f32_e32 v57, v32, v47
	v_mul_f32_e32 v47, v8, v48
	s_waitcnt lgkmcnt(1)
	v_mul_f32_e32 v7, v7, v53
	v_pk_mul_f32 v[8:9], v[46:47], v[6:7]
	s_waitcnt lgkmcnt(0)
	v_pk_mul_f32 v[2:3], v[2:3], v[4:5]
	v_mul_f32_e32 v55, v16, v49
	v_pk_mul_f32 v[48:49], v[2:3], v[8:9]
	v_mov_b32_e32 v238, v48
	v_mov_b32_e32 v58, v48
	s_nop 1
	v_permlane32_swap_b32_e32 v238, v58
	s_nop 0
	v_cndmask_b32_e64 v58, v238, v58, s[0:1]
	v_mul_f32_e32 v2, v9, v5
	v_cndmask_b32_e64 v2, v9, v2, s[0:1]
	v_mul_f32_e32 v3, v10, v2
	v_mul_f32_e32 v8, v31, v2
	s_waitcnt lgkmcnt(0)
	v_mul_f32_e32 v2, v49, v58
	v_cndmask_b32_e64 v2, v49, v2, s[0:1]
	v_mul_f32_e32 v5, v30, v3
	v_mul_f32_e32 v9, v29, v3
	v_mul_f32_e32 v3, v6, v2
	v_mul_f32_e32 v6, v46, v3
	v_mul_f32_e32 v4, v4, v6
	v_mul_f32_e32 v10, v24, v2
	v_mul_f32_e32 v2, v22, v6
	v_mul_f32_e32 v6, v47, v53
	v_mul_f32_e32 v7, v28, v5
	v_cndmask_b32_e64 v6, v47, v6, s[0:1]
	v_mul_f32_e32 v5, v27, v5
	v_mul_f32_e32 v7, v26, v7
	v_mul_f32_e32 v3, v25, v3
	v_mul_f32_e32 v4, v23, v4
	v_mul_f32_e32 v47, v15, v6
	v_cndmask_b32_e64 v14, 0, v14, s[40:41]
	v_cndmask_b32_e64 v17, 0, v17, s[44:45]
	v_cvt_pk_bf16_f32 v2, v4, v2
	v_cvt_pk_bf16_f32 v3, v3, v10
	v_cvt_pk_bf16_f32 v4, v7, v5
	v_cvt_pk_bf16_f32 v5, v9, v8
	v_mul_f32_e32 v53, v11, v47
	v_mul_f32_e32 v56, v17, v33
	v_mfma_f32_32x32x16_bf16 v[18:33], v[18:21], v[2:5], 0
	v_mul_f32_e32 v46, v14, v54
	v_mul_f32_e32 v54, v12, v53
	v_mul_f32_e32 v59, v13, v6
	v_mfma_f32_32x32x16_bf16 v[2:17], v[42:45], v[2:5], 0
	v_mul_f32_e32 v43, v52, v47
	v_mul_f32_e32 v42, v51, v53
	v_mul_f32_e32 v44, v50, v54
	v_cvt_pk_bf16_f32 v42, v44, v42
	v_cvt_pk_bf16_f32 v43, v43, v59
	v_cvt_pk_bf16_f32 v44, v46, v57
	v_cvt_pk_bf16_f32 v45, v56, v55
	s_nop 1
	v_mfma_f32_32x32x16_bf16 v[18:33], v[34:37], v[42:45], v[18:33]
	v_mul_f32_e32 v34, v48, v58
	v_mul_f32_e32 v131, v34, v49
	v_cmp_gt_f32_e32 vcc, s88, v131
	s_cmp_eq_u64 vcc, exec
	v_mfma_f32_32x32x16_bf16 v[2:17], v[38:41], v[42:45], v[2:17]
	s_cbranch_scc1 .LBB0_553
	s_cmp_eq_u32 s90, 0
	s_cbranch_scc1 .LBB0_556
	s_lshl_b32 s72, s59, 8
	s_lshl_b32 s77, s59, 15
	s_sub_i32 s59, s72, 32
	v_add_u32_e32 v34, s72, v204
	s_lshl_b32 s72, s58, 7
	s_sub_i32 s72, s77, s72
	s_add_i32 s93, s86, s91
	v_subrev_u32_e32 v165, s58, v34
	v_add_u32_e32 v167, s72, v205
	s_sub_i32 s77, s59, s58
	s_nop 7
	v_mov_b64_e32 v[34:35], v[2:3]
	v_mov_b64_e32 v[36:37], v[4:5]
	v_mov_b64_e32 v[38:39], v[6:7]
	v_mov_b64_e32 v[40:41], v[8:9]
	v_mov_b64_e32 v[42:43], v[10:11]
	v_mov_b64_e32 v[44:45], v[12:13]
	v_mov_b64_e32 v[46:47], v[14:15]
	v_mov_b64_e32 v[48:49], v[16:17]
	v_mov_b64_e32 v[50:51], v[18:19]
	v_mov_b64_e32 v[52:53], v[20:21]
	v_mov_b64_e32 v[54:55], v[22:23]
	v_mov_b64_e32 v[56:57], v[24:25]
	v_mov_b64_e32 v[58:59], v[26:27]
	v_mov_b64_e32 v[60:61], v[28:29]
	v_mov_b64_e32 v[62:63], v[30:31]
	v_mov_b64_e32 v[64:65], v[32:33]
	v_add_u32_e32 v255, s87, v165
	v_lshrrev_b32_e32 v255, 1, v255
	v_bitop3_b32 v240, v255, v1, 7 bitop3:0x6c
	v_lshl_add_u32 v240, v240, 4, v167
	ds_read_b128 v[240:243], v240
	v_bitop3_b32 v244, v255, v143, 7 bitop3:0x6c
	v_lshl_add_u32 v244, v244, 4, v167
	ds_read_b128 v[244:247], v244
	v_bitop3_b32 v248, v255, v147, 7 bitop3:0x6c
	v_lshl_add_u32 v248, v248, 4, v167
	ds_read_b128 v[248:251], v248
	v_bitop3_b32 v252, v255, v149, 7 bitop3:0x6c
	v_lshl_add_u32 v252, v252, 4, v167
	ds_read_b128 v[252:255], v252
	s_branch .LBB0_545
